# P4: a pass that writes y touches its z rows in the pass header (L2 prefetch into a dead VGPR)
# baseline (speedup 1.0000x reference)
.LBB0_640:
	s_cmp_lg_u32 s67, s62
	s_cbranch_scc1 .Lzp_skip
	s_add_i32 s78, s65, s63
	s_ashr_i32 s79, s78, 31
	s_lshl_b64 s[78:79], s[78:79], 23
	v_lshl_add_u64 v[4:5], v[170:171], 0, s[78:79]
	s_add_i32 s78, s66, s63
	s_ashr_i32 s79, s78, 31
	s_lshl_b64 s[78:79], s[78:79], 23
	global_load_dword v241, v[4:5], off
	global_load_dword v241, v[4:5], off offset:64
	v_lshl_add_u64 v[4:5], v[170:171], 0, s[78:79]
	global_load_dword v241, v[4:5], off
	global_load_dword v241, v[4:5], off offset:64
